# HGRN: output-norm gain kept in registers across the chunk loop, do_final no longer drains the next chunk prefetch (on top of nt stores)
# speedup vs baseline: 1.0119x; 1.0119x over previous
; __device__ __forceinline__ unsigned cvtpk(float lo, float hi) { f32x2_t v = {lo, hi}; bf16x2_t b = __builtin_convertvector(v, bf16x2_t); return __builtin_bit_cast(unsigned, b); }
; __device__ __forceinline__ float sigm(float x) { return __builtin_amdgcn_rcpf(1.f + __builtin_amdgcn_exp2f(-x * LOG2E)); }
; __device__ __forceinline__ int crow(int r, int hi) { return (r & 3) + 8 * (r >> 2) + 4 * hi; }
; #define MFMA32(a, b, c) __builtin_amdgcn_mfma_f32_32x32x16_bf16((a), (b), (c), 0, 0, 0)
; __device__ __forceinline__ void hgrn_unit(ldsp L, int bh, const bf16* __restrict__ hq, const bf16* __restrict__ hf, const bf16* __restrict__ hv, const bf16* __restrict__ hg, bf16* __restrict__ yb, ...
;     const int tid = threadIdx.x, lane = tid & 63, r32 = lane & 31, hi = lane >> 5, w = __builtin_amdgcn_readfirstlane(tid >> 6);
;     const int b = bh >> 3, h = bh & 7;
;     const size_t tok0 = (size_t)b * SEQ;
;     const bool prep = w >= 4;
;     const int pt = tid & 255, cpl = lane & 15, tq = lane >> 4, k0 = 2 * (16 * (w & 3) + cpl);
;     const float lb0 = sigm(lbl[h * 128 + k0] - lbl[1024 + h * 128 + k0]), lb1 = sigm(lbl[h * 128 + k0 + 1] - lbl[1024 + h * 128 + k0 + 1]);
;     const int vrow = pt >> 3, vc8 = pt & 7;
;     f32x16 S[4]; S[0] = f32x16{}; S[1] = f32x16{}; S[2] = f32x16{}; S[3] = f32x16{};
;     const int vb = w & 3;
;     unsigned qw[8], fw[8]; u32x4 v0r = {0u, 0u, 0u, 0u}, v1r = {0u, 0u, 0u, 0u}, g0r = {0u, 0u, 0u, 0u}, g1r = {0u, 0u, 0u, 0u};
; #pragma unroll
;     for (int i = 0; i < 8; ++i) { qw[i] = 0u; fw[i] = 0u; }
;     ...
;             w0[k] = cvtpk(ov[2 * k] * rs * gnorm[v0 + 2 * k] * a, ov[2 * k + 1] * rs * gnorm[v0 + 2 * k + 1] * c2);
;             w1[k] = cvtpk(ov[8 + 2 * k] * rs * gnorm[v0 + 8 + 2 * k] * a1, ov[8 + 2 * k + 1] * rs * gnorm[v0 + 8 + 2 * k + 1] * c1); }
;         *(u32x4*)(yb + off) = w0; *(u32x4*)(yb + off + 8) = w1;
;     };
;     auto do_mfma = [&](int c) {
;         const ldsp B = L + (c & 1) * H_BUF;
;         const ldsp Qt = B + H_QT + r32 * H_QP, Kt = B + H_KT + r32 * H_QP;
;         f32x16 D = f32x16{};
; #pragma unroll
;         for (int kk = 0; kk < 8; ++kk) { const bf16x8 a = lds_ld<bf16x8>(Kt + (16 * kk + 8 * hi) * 2), bq = lds_ld<bf16x8>(Qt + (16 * kk + 8 * hi) * 2); D = MFMA32(a, bq, D); }
; #pragma unroll
;         for (int r = 0; r < 16; ++r) if (crow(r, hi) > r32) D[r] = 0.f;
.LBB0_730:
	v_lshrrev_b32_e32 v1, 5, v204
	v_lshlrev_b32_e32 v2, 2, v1
	v_and_b32_e32 v0, 31, v220
	v_or_b32_e32 v3, 2, v2
	v_cmp_gt_u32_e64 s[4:5], v3, v0
	v_or_b32_e32 v3, 3, v2
	v_cmp_gt_u32_e64 s[6:7], v3, v0
	v_or_b32_e32 v3, 8, v2
	v_cmp_gt_u32_e64 s[8:9], v3, v0
	v_or_b32_e32 v3, 9, v2
	v_cmp_gt_u32_e64 s[10:11], v3, v0
	v_or_b32_e32 v3, 10, v2
	v_cmp_gt_u32_e64 s[12:13], v3, v0
	v_or_b32_e32 v3, 11, v2
	v_cmp_gt_u32_e64 s[14:15], v3, v0
	v_or_b32_e32 v3, 16, v2
	v_cmp_gt_u32_e64 s[16:17], v3, v0
	v_or_b32_e32 v3, 17, v2
	v_cmp_gt_u32_e64 s[18:19], v3, v0
	v_or_b32_e32 v3, 18, v2
	v_cmp_gt_u32_e64 s[20:21], v3, v0
	v_or_b32_e32 v3, 19, v2
	v_cmp_gt_u32_e64 s[22:23], v3, v0
	v_or_b32_e32 v3, 24, v2
	v_cmp_gt_u32_e64 s[24:25], v3, v0
	v_or_b32_e32 v3, 25, v2
	v_cmp_gt_u32_e64 s[0:1], v2, v0
	v_cmp_lt_u32_e64 s[2:3], v2, v0
	v_cmp_gt_u32_e64 s[26:27], v3, v0
	v_or_b32_e32 v3, 26, v2
	v_or_b32_e32 v2, 27, v2
	v_cmp_gt_u32_e64 s[28:29], v3, v0
	v_cmp_gt_u32_e64 s[30:31], v2, v0
	v_bfe_u32 v2, v220, 2, 2
	v_lshlrev_b32_e32 v3, 2, v220
	v_mul_u32_u24_e32 v213, 0x140, v2
	v_and_b32_e32 v2, 16, v220
	v_and_b32_e32 v3, 12, v3
	v_or3_b32 v2, v2, v3, s33
	v_mul_u32_u24_e32 v211, 0x110, v0
	v_lshlrev_b32_e32 v214, 1, v2
	v_or_b32_e32 v2, s33, v0
	v_mul_u32_u24_e32 v219, 0x50, v0
	v_lshlrev_b32_e32 v0, 4, v220
	v_and_b32_e32 v164, 0x70, v0
	v_mov_b32_e32 v173, 0
	v_lshlrev_b32_e32 v168, 2, v164
	v_mov_b32_e32 v169, v173
	v_lshl_add_u64 v[170:171], s[42:43], 0, v[168:169]
	global_load_dwordx4 v[234:237], v[170:171], off
	global_load_dwordx4 v[238:241], v[170:171], off offset:32
	global_load_dwordx4 v[242:245], v[170:171], off offset:16
	global_load_dwordx4 v[246:249], v[170:171], off offset:48
	v_readlane_b32 s42, v250, 11
	v_lshlrev_b32_e32 v212, 4, v1
	v_mul_u32_u24_e32 v215, 0x500, v1
	v_lshlrev_b32_e32 v216, 3, v1
	v_lshlrev_b32_e32 v217, 11, v1
	v_mul_u32_u24_e32 v221, 0xa00, v1
	v_lshlrev_b64 v[0:1], 1, v[162:163]
	v_readlane_b32 s43, v250, 12
	v_lshlrev_b32_e32 v218, 2, v2
	v_lshlrev_b32_e32 v172, 1, v164
	v_lshl_add_u64 v[2:3], s[42:43], 0, v[0:1]
	v_lshl_add_u64 v[174:175], v[2:3], 0, v[172:173]
	s_lshl_b64 s[42:43], s[68:69], 22
	v_lshlrev_b64 v[2:3], 11, v[10:11]
	v_lshl_add_u64 v[2:3], s[42:43], 0, v[2:3]
	v_lshl_add_u64 v[4:5], v[162:163], 0, v[14:15]
	v_lshl_add_u64 v[2:3], v[4:5], 1, v[2:3]
	v_lshl_add_u64 v[184:185], s[64:65], 0, v[2:3]
	v_lshlrev_b64 v[2:3], 11, v[8:9]
	v_lshl_add_u64 v[2:3], s[42:43], 0, v[2:3]
	v_lshl_or_b32 v2, v13, 1, v2
	v_lshl_add_u64 v[186:187], s[64:65], 0, v[2:3]
	v_lshlrev_b32_e32 v2, 8, v220
	v_mbcnt_lo_u32_b32 v16, -1, 0
	v_and_b32_e32 v2, 0xf800, v2
	v_lshlrev_b32_e32 v3, 5, v190
	v_mbcnt_hi_u32_b32 v16, -1, v16
	v_or3_b32 v2, s42, v2, v3
	v_mov_b32_e32 v3, s43
	v_lshl_add_u64 v[0:1], s[64:65], 0, v[0:1]
	v_mov_b32_e32 v140, v173
	v_mov_b32_e32 v141, v173
	v_mov_b32_e32 v14, v173
	v_mov_b32_e32 v15, v173
	v_and_or_b32 v16, v16, 64, v58
	v_cmp_gt_u32_e64 s[34:35], 16, v204
	v_lshlrev_b32_e32 v222, 2, v12
	v_lshlrev_b32_e32 v204, 9, v10
	v_or_b32_e32 v172, 0xffffffe0, v10
	v_lshl_add_u64 v[188:189], v[0:1], 0, v[2:3]
	v_mov_b32_e32 v142, v173
	v_mov_b32_e32 v143, v173
	v_mov_b32_e32 v0, v173
	v_mov_b32_e32 v1, v173
	v_mov_b32_e32 v2, v173
	v_mov_b32_e32 v3, v173
	v_mov_b32_e32 v4, v173
	v_mov_b32_e32 v5, v173
	v_mov_b32_e32 v6, v173
	v_mov_b32_e32 v7, v173
	v_mov_b32_e32 v8, v173
	v_mov_b32_e32 v9, v173
	v_mov_b32_e32 v10, v173
	v_mov_b32_e32 v11, v173
	v_mov_b32_e32 v12, v173
	v_mov_b32_e32 v13, v173
	v_lshlrev_b32_e32 v224, 2, v16
	v_mov_b64_e32 v[30:31], v[14:15]
	v_mov_b64_e32 v[46:47], v[14:15]
	v_mov_b64_e32 v[62:63], v[14:15]
	v_mov_b64_e32 v[136:137], v[140:141]
	v_lshrrev_b32_e32 v159, 3, v220
	s_mov_b64 s[96:97], s[70:71]
	v_mov_b32_e32 v176, v167
	v_mov_b32_e32 v177, v167
	v_mov_b32_e32 v178, v154
	v_mov_b32_e32 v179, v154
	v_mov_b32_e32 v180, v152
	v_mov_b32_e32 v181, v152
	v_mov_b32_e32 v182, v166
	v_mov_b32_e32 v183, v166
	v_add3_u32 v169, 0, v204, v168
	s_mov_b32 s72, -1
	s_mov_b64 s[42:43], 0
	v_mov_b32_e32 v223, 0x358637bd
	v_mov_b64_e32 v[28:29], v[12:13]
	v_mov_b64_e32 v[26:27], v[10:11]
	v_mov_b64_e32 v[24:25], v[8:9]
	v_mov_b64_e32 v[22:23], v[6:7]
	v_mov_b64_e32 v[20:21], v[4:5]
	v_mov_b64_e32 v[18:19], v[2:3]
	v_mov_b64_e32 v[16:17], v[0:1]
	v_mov_b64_e32 v[44:45], v[12:13]
	v_mov_b64_e32 v[42:43], v[10:11]
	v_mov_b64_e32 v[40:41], v[8:9]
	v_mov_b64_e32 v[38:39], v[6:7]
	v_mov_b64_e32 v[36:37], v[4:5]
	v_mov_b64_e32 v[34:35], v[2:3]
	v_mov_b64_e32 v[32:33], v[0:1]
	v_mov_b64_e32 v[60:61], v[12:13]
	v_mov_b64_e32 v[58:59], v[10:11]
	v_mov_b64_e32 v[56:57], v[8:9]
	v_mov_b64_e32 v[54:55], v[6:7]
	v_mov_b64_e32 v[52:53], v[4:5]
	v_mov_b64_e32 v[50:51], v[2:3]
	v_mov_b64_e32 v[48:49], v[0:1]
	v_mov_b64_e32 v[138:139], v[142:143]
	s_waitcnt lgkmcnt(0)
	s_barrier
	s_add_i32 s33, s72, 1
	s_mov_b64 s[68:69], -1
	s_and_b64 vcc, exec, s[40:41]
	s_cbranch_vccz .LBB0_732

; __device__ __forceinline__ unsigned cvtpk(float lo, float hi) { f32x2_t v = {lo, hi}; bf16x2_t b = __builtin_convertvector(v, bf16x2_t); return __builtin_bit_cast(unsigned, b); }
; __device__ __forceinline__ float bflo(unsigned w) { return __uint_as_float(w << 16); }
; __device__ __forceinline__ float bfhi(unsigned w) { return __uint_as_float(w & 0xffff0000u); }
; #define DPP_F(v, ctrl) __builtin_bit_cast(float, __builtin_amdgcn_update_dpp(0, __builtin_bit_cast(int, (v)), (ctrl), 0xf, 0xf, true))
; __device__ __forceinline__ void hgrn_unit(ldsp L, int bh, const bf16* __restrict__ hq, const bf16* __restrict__ hf, const bf16* __restrict__ hv, const bf16* __restrict__ hg, bf16* __restrict__ yb, ...
;     ...
;     auto do_final = [&](int c) {
;         const ldsp Ob = L + (c & 1) * H_BUF + H_O;
;         const int t = pt >> 3, v0 = 16 * (pt & 7);
;         float ov[16]; float ssq = 0.f;
; #pragma unroll
;         for (int i = 0; i < 4; ++i) { const f32x4 a = lds_ld<f32x4>(Ob + (t * 128 + v0 + 4 * i) * 4);
; #pragma unroll
;             for (int k = 0; k < 4; ++k) { ov[4 * i + k] = a[k]; ssq += a[k] * a[k]; } }
;         ssq += DPP_F(ssq, 0xB1); ssq += DPP_F(ssq, 0x4E); ssq += DPP_F(ssq, 0x141);
;         const float rs = rsqrtf(ssq * (1.f / 128.f) + EPS);
;         const size_t off = (tok0 + 32 * c + t) * 1024 + h * 128 + v0;
;         const u32x4 g0 = g0r, g1 = g1r;
;         u32x4 w0, w1;
; #pragma unroll
;         for (int k = 0; k < 4; ++k) { const float a = bflo(g0[k]), c2 = bfhi(g0[k]), a1 = bflo(g1[k]), c1 = bfhi(g1[k]);
;             w0[k] = cvtpk(ov[2 * k] * rs * gnorm[v0 + 2 * k] * a, ov[2 * k + 1] * rs * gnorm[v0 + 2 * k + 1] * c2);
;             w1[k] = cvtpk(ov[8 + 2 * k] * rs * gnorm[v0 + 8 + 2 * k] * a1, ov[8 + 2 * k + 1] * rs * gnorm[v0 + 8 + 2 * k + 1] * c1); }
;         *(u32x4*)(yb + off) = w0; *(u32x4*)(yb + off + 8) = w1;
;     };
.LBB0_736:
	s_cmp_lg_u32 s42, 0x3f0000
	s_cbranch_scc1 .Lhg_nowait
	s_waitcnt vmcnt(0)
.Lhg_nowait:
	s_bitcmp1_b32 s72, 0
	s_cselect_b32 s68, 0xd600, 0
	v_add_u32_e32 v92, s68, v169
	ds_read_b128 v[80:83], v92 offset:38400
	ds_read_b128 v[84:87], v92 offset:38432
	ds_read_b128 v[88:91], v92 offset:38448
	ds_read_b128 v[92:95], v92 offset:38416
	s_mov_b32 s68, 0x800000
	v_lshlrev_b32_e32 v96, 16, v140
	s_waitcnt lgkmcnt(3)
	v_mul_f32_e32 v107, v81, v81
	v_fmac_f32_e32 v107, v80, v80
	v_fmac_f32_e32 v107, v82, v82
	v_fmac_f32_e32 v107, v83, v83
	s_waitcnt lgkmcnt(0)
	v_fmac_f32_e32 v107, v92, v92
	v_fmac_f32_e32 v107, v93, v93
	v_fmac_f32_e32 v107, v94, v94
	v_pk_mul_f32 v[110:111], v[84:85], v[84:85]
	v_fmac_f32_e32 v107, v95, v95
	v_add_f32_e32 v107, v110, v107
	v_pk_mul_f32 v[108:109], v[86:87], v[86:87]
	v_add_f32_e32 v107, v111, v107
	v_add_f32_e32 v107, v108, v107
	v_pk_mul_f32 v[114:115], v[88:89], v[88:89]
	v_add_f32_e32 v107, v109, v107
	v_add_f32_e32 v107, v114, v107
	v_pk_mul_f32 v[112:113], v[90:91], v[90:91]
	v_add_f32_e32 v107, v115, v107
	v_add_f32_e32 v107, v112, v107
	v_add_f32_e32 v107, v113, v107
	v_and_b32_e32 v97, 0xffff0000, v140
	v_lshlrev_b32_e32 v100, 16, v141
	v_add_f32_dpp v107, v107, v107 quad_perm:[1,0,3,2] row_mask:0xf bank_mask:0xf bound_ctrl:1
	v_and_b32_e32 v101, 0xffff0000, v141
	v_and_b32_e32 v109, 0xffff0000, v143
	v_add_f32_dpp v107, v107, v107 quad_perm:[2,3,0,1] row_mask:0xf bank_mask:0xf bound_ctrl:1
	v_lshlrev_b32_e32 v104, 16, v142
	v_and_b32_e32 v105, 0xffff0000, v142
	v_add_f32_dpp v107, v107, v107 row_half_mirror row_mask:0xf bank_mask:0xf bound_ctrl:1
	v_fmamk_f32 v107, v107, 0x3c000000, v223
	v_mul_f32_e32 v108, 0x4b800000, v107
	v_cmp_gt_f32_e32 vcc, s68, v107
	v_lshlrev_b32_e32 v98, 16, v136
	v_and_b32_e32 v99, 0xffff0000, v136
	v_cndmask_b32_e32 v107, v107, v108, vcc
	v_rsq_f32_e32 v110, v107
	v_lshlrev_b32_e32 v108, 16, v143
	v_lshlrev_b32_e32 v102, 16, v137
	v_and_b32_e32 v103, 0xffff0000, v137
	v_mul_f32_e32 v111, 0x45800000, v110
	v_cndmask_b32_e32 v110, v110, v111, vcc
	v_pk_mul_f32 v[80:81], v[80:81], v[110:111] op_sel_hi:[1,0]
	v_pk_mul_f32 v[82:83], v[82:83], v[110:111] op_sel_hi:[1,0]
	v_pk_mul_f32 v[94:95], v[94:95], v[110:111] op_sel_hi:[1,0]
	v_pk_mul_f32 v[92:93], v[92:93], v[110:111] op_sel_hi:[1,0]
	v_pk_mul_f32 v[84:85], v[84:85], v[110:111] op_sel_hi:[1,0]
	v_pk_mul_f32 v[86:87], v[86:87], v[110:111] op_sel_hi:[1,0]
	v_pk_mul_f32 v[88:89], v[88:89], v[110:111] op_sel_hi:[1,0]
	v_lshlrev_b32_e32 v106, 16, v138
	v_and_b32_e32 v107, 0xffff0000, v138
	v_pk_mul_f32 v[64:65], v[234:235], v[80:81]
	v_pk_mul_f32 v[66:67], v[236:237], v[82:83]
	v_pk_mul_f32 v[74:75], v[244:245], v[94:95]
	v_pk_mul_f32 v[72:73], v[242:243], v[92:93]
	v_pk_mul_f32 v[64:65], v[64:65], v[96:97]
	v_pk_mul_f32 v[66:67], v[66:67], v[100:101]
	v_pk_mul_f32 v[74:75], v[74:75], v[108:109]
	v_pk_mul_f32 v[72:73], v[72:73], v[104:105]
	v_cvt_pk_bf16_f32 v64, v64, v65
	v_cvt_pk_bf16_f32 v65, v66, v67
	v_cvt_pk_bf16_f32 v67, v74, v75
	v_pk_mul_f32 v[74:75], v[90:91], v[110:111] op_sel_hi:[1,0]
	v_pk_mul_f32 v[68:69], v[238:239], v[84:85]
	v_pk_mul_f32 v[70:71], v[240:241], v[86:87]
	v_cvt_pk_bf16_f32 v66, v72, v73
	v_lshlrev_b32_e32 v72, 16, v139
	v_and_b32_e32 v73, 0xffff0000, v139
	v_pk_mul_f32 v[74:75], v[248:249], v[74:75]
	v_pk_mul_f32 v[68:69], v[68:69], v[98:99]
	v_pk_mul_f32 v[70:71], v[70:71], v[102:103]
	v_pk_mul_f32 v[72:73], v[74:75], v[72:73]
	v_cvt_pk_bf16_f32 v68, v68, v69
	v_cvt_pk_bf16_f32 v69, v70, v71
	v_cvt_pk_bf16_f32 v71, v72, v73
	v_lshl_add_u64 v[72:73], s[36:37], 0, v[172:173]
	v_pk_mul_f32 v[76:77], v[246:247], v[88:89]
	v_lshlrev_b64 v[72:73], 11, v[72:73]
	v_pk_mul_f32 v[76:77], v[76:77], v[106:107]
	v_lshl_add_u64 v[72:73], v[174:175], 0, v[72:73]
	v_cvt_pk_bf16_f32 v70, v76, v77
	global_store_dwordx4 v[72:73], v[64:67], off
	global_store_dwordx4 v[72:73], v[68:71], off offset:16
